# combo1 + final RMSNorm phase de-serialised: gain chunks loaded once, a row's sum and 8 chunks in flight together, next row issued before the last store
# baseline (speedup 1.0000x reference)
; __device__ __forceinline__ void final_phase(const bf16_t* xb, float* out, const float* gain, const unsigned long long* ss) {
;     int tid_ = threadIdx.x; asm volatile("" : "+v"(tid_));
;     const int lane = tid_ & 63, wave = __builtin_amdgcn_readfirstlane(tid_ >> 6);
;     const int gw = blockIdx.x * 8 + wave, NGW = gridDim.x * 8;
;     for (int row = gw; row < MTOK; row += NGW) {
;         const u32x2* xr = (const u32x2*)(xb + (size_t)row * DM) + lane;
;         f32x4* o = (f32x4*)(out + (size_t)row * DM) + lane;
;         const float r = rsqrtf((float)ss[row] * (1.f / (DM * 16777216.f)) + EPS);
; #pragma unroll
;         for (int j = 0; j < 8; ++j) { const u32x2 w = xr[64 * j]; const f32x4 g = ((const f32x4*)gain)[lane + 64 * j];
.LBB0_732:
	v_readlane_b32 s6, v250, 11
	v_readlane_b32 s7, v250, 12
	v_readlane_b32 s1, v250, 2
	v_readfirstlane_b32 s0, v199
	s_ashr_i32 s0, s0, 6
	s_add_i32 s2, s0, s1
	s_cmpk_gt_i32 s2, 0x3fff
	s_cbranch_scc1 .LBB0_735
	s_load_dwordx4 s[12:15], s[6:7], 0x78
	s_load_dwordx2 s[4:5], s[6:7], 0x88
	v_and_b32_e32 v12, 63, v199
	v_mov_b32_e32 v1, 0
	v_lshlrev_b32_e32 v0, 4, v12
	s_waitcnt lgkmcnt(0)
	v_lshl_add_u64 v[2:3], s[12:13], 0, v[0:1]
	s_mov_b64 s[0:1], 0x1400
	v_lshl_add_u64 v[6:7], v[2:3], 0, s[0:1]
	s_mov_b64 s[0:1], 0x1800
	v_lshl_add_u64 v[8:9], v[2:3], 0, s[0:1]
	s_mov_b64 s[0:1], 0x1c00
	s_ashr_i32 s3, s2, 31
	v_lshl_add_u64 v[10:11], v[2:3], 0, s[0:1]
	s_lshl_b64 s[0:1], s[2:3], 3
	v_readlane_b32 s16, v250, 41
	s_add_u32 s10, s0, 0x2b100000
	v_readlane_b32 s17, v250, 42
	s_addc_u32 s11, s1, 0
	s_ashr_i32 s17, s16, 31
	s_lshl_b64 s[6:7], s[2:3], 12
	s_lshl_b64 s[0:1], s[16:17], 3
	v_lshl_or_b32 v12, v12, 3, s6
	v_mov_b32_e32 v13, s7
	s_lshl_b64 s[6:7], s[16:17], 12
	s_lshl_b64 s[12:13], s[2:3], 13
	s_add_u32 s12, s14, s12
	s_addc_u32 s13, s15, s13
	s_mov_b64 s[8:9], 0x1000
	v_lshl_add_u64 v[14:15], s[12:13], 0, v[0:1]
	v_lshl_add_u64 v[4:5], v[2:3], 0, s[8:9]
	v_lshl_add_u64 v[14:15], v[14:15], 0, s[8:9]
	s_lshl_b64 s[8:9], s[16:17], 13
	v_mov_b32_e32 v0, 0x358637bd
	s_mov_b32 s3, 0x800000
	s_mov_b32 s12, 0x15c00000
	global_load_dwordx4 v[36:39], v[2:3], off
	global_load_dwordx4 v[40:43], v[2:3], off offset:1024
	global_load_dwordx4 v[44:47], v[2:3], off offset:2048
	global_load_dwordx4 v[48:51], v[2:3], off offset:3072
	global_load_dwordx4 v[52:55], v[4:5], off
	global_load_dwordx4 v[56:59], v[6:7], off
	global_load_dwordx4 v[60:63], v[8:9], off
	global_load_dwordx4 v[64:67], v[10:11], off
	v_lshl_add_u64 v[16:17], s[4:5], 0, v[12:13]
	s_add_u32 s14, s4, s10
	s_addc_u32 s15, s5, s11
	v_add_co_u32_e32 v20, vcc, s12, v16
	s_nop 1
	v_addc_co_u32_e32 v21, vcc, 0, v17, vcc
	global_load_dwordx2 v[100:101], v1, s[14:15]
	global_load_dwordx2 v[68:69], v[20:21], off
	global_load_dwordx2 v[70:71], v[20:21], off offset:512
	global_load_dwordx2 v[72:73], v[20:21], off offset:1024
	global_load_dwordx2 v[74:75], v[20:21], off offset:1536
	global_load_dwordx2 v[76:77], v[20:21], off offset:2048
	global_load_dwordx2 v[78:79], v[20:21], off offset:2560
	global_load_dwordx2 v[80:81], v[20:21], off offset:3072
	global_load_dwordx2 v[82:83], v[20:21], off offset:3584
; __device__ __forceinline__ float bf_lo(unsigned w) { return __uint_as_float(w << 16); }
; __device__ __forceinline__ float bf_hi(unsigned w) { return __uint_as_float(w & 0xffff0000u); }
; __device__ __forceinline__ void final_phase(const bf16_t* xb, float* out, const float* gain, const unsigned long long* ss) {
;     ...
;     for (int row = gw; row < MTOK; row += NGW) {
;         const u32x2* xr = (const u32x2*)(xb + (size_t)row * DM) + lane;
;         f32x4* o = (f32x4*)(out + (size_t)row * DM) + lane;
;         const float r = rsqrtf((float)ss[row] * (1.f / (DM * 16777216.f)) + EPS);
; #pragma unroll
;         for (int j = 0; j < 8; ++j) { const u32x2 w = xr[64 * j]; const f32x4 g = ((const f32x4*)gain)[lane + 64 * j];
;             f32x4 v; v.x = bf_lo(w.x) * r * g.x; v.y = bf_hi(w.x) * r * g.y; v.z = bf_lo(w.y) * r * g.z; v.w = bf_hi(w.y) * r * g.w; o[64 * j] = v; }
;     }
.LBB0_734:
	s_waitcnt vmcnt(8)
	v_mov_b32_e32 v22, v100
	v_mov_b32_e32 v23, v101
	v_ffbh_u32_e32 v28, v23
	v_min_u32_e32 v28, 32, v28
	v_lshlrev_b64 v[22:23], v28, v[22:23]
	v_min_u32_e32 v22, 1, v22
	v_or_b32_e32 v22, v23, v22
	v_cvt_f32_u32_e32 v22, v22
	v_sub_u32_e32 v28, 32, v28
	v_ldexp_f32 v22, v22, v28
	v_fmamk_f32 v22, v22, 0x2e000000, v0
	v_mul_f32_e32 v23, 0x4b800000, v22
	v_cmp_gt_f32_e32 vcc, s3, v22
	s_nop 1
	v_cndmask_b32_e32 v22, v22, v23, vcc
	v_rsq_f32_e32 v22, v22
	s_nop 0
	v_mul_f32_e32 v23, 0x45800000, v22
	v_cndmask_b32_e32 v22, v22, v23, vcc
	s_add_i32 s2, s2, s16
	s_add_u32 s10, s10, s0
	s_addc_u32 s11, s11, s1
	v_lshl_add_u64 v[12:13], v[12:13], 0, s[6:7]
	s_waitcnt vmcnt(7)
	v_lshlrev_b32_e32 v26, 16, v68
	v_and_b32_e32 v27, 0xffff0000, v68
	v_lshlrev_b32_e32 v24, 16, v69
	v_and_b32_e32 v25, 0xffff0000, v69
	v_pk_mul_f32 v[26:27], v[22:23], v[26:27] op_sel_hi:[0,1]
	v_pk_mul_f32 v[24:25], v[22:23], v[24:25] op_sel_hi:[0,1]
	v_pk_mul_f32 v[16:17], v[36:37], v[26:27]
	v_pk_mul_f32 v[18:19], v[38:39], v[24:25]
	global_store_dwordx4 v[14:15], v[16:19], off offset:-4096
	s_waitcnt vmcnt(7)
	v_lshlrev_b32_e32 v26, 16, v70
	v_and_b32_e32 v27, 0xffff0000, v70
	v_lshlrev_b32_e32 v24, 16, v71
	v_and_b32_e32 v25, 0xffff0000, v71
	v_pk_mul_f32 v[26:27], v[22:23], v[26:27] op_sel_hi:[0,1]
	v_pk_mul_f32 v[24:25], v[22:23], v[24:25] op_sel_hi:[0,1]
	v_pk_mul_f32 v[16:17], v[40:41], v[26:27]
	v_pk_mul_f32 v[18:19], v[42:43], v[24:25]
	global_store_dwordx4 v[14:15], v[16:19], off offset:-3072
	s_waitcnt vmcnt(7)
	v_lshlrev_b32_e32 v26, 16, v72
	v_and_b32_e32 v27, 0xffff0000, v72
	v_lshlrev_b32_e32 v24, 16, v73
	v_and_b32_e32 v25, 0xffff0000, v73
	v_pk_mul_f32 v[26:27], v[22:23], v[26:27] op_sel_hi:[0,1]
	v_pk_mul_f32 v[24:25], v[22:23], v[24:25] op_sel_hi:[0,1]
	v_pk_mul_f32 v[16:17], v[44:45], v[26:27]
	v_pk_mul_f32 v[18:19], v[46:47], v[24:25]
	global_store_dwordx4 v[14:15], v[16:19], off offset:-2048
	s_waitcnt vmcnt(7)
	v_lshlrev_b32_e32 v26, 16, v74
	v_and_b32_e32 v27, 0xffff0000, v74
	v_lshlrev_b32_e32 v24, 16, v75
	v_and_b32_e32 v25, 0xffff0000, v75
	v_pk_mul_f32 v[26:27], v[22:23], v[26:27] op_sel_hi:[0,1]
	v_pk_mul_f32 v[24:25], v[22:23], v[24:25] op_sel_hi:[0,1]
	v_pk_mul_f32 v[16:17], v[48:49], v[26:27]
	v_pk_mul_f32 v[18:19], v[50:51], v[24:25]
	global_store_dwordx4 v[14:15], v[16:19], off offset:-1024
	s_waitcnt vmcnt(7)
	v_lshlrev_b32_e32 v26, 16, v76
	v_and_b32_e32 v27, 0xffff0000, v76
	v_lshlrev_b32_e32 v24, 16, v77
	v_and_b32_e32 v25, 0xffff0000, v77
	v_pk_mul_f32 v[26:27], v[22:23], v[26:27] op_sel_hi:[0,1]
	v_pk_mul_f32 v[24:25], v[22:23], v[24:25] op_sel_hi:[0,1]
	v_pk_mul_f32 v[16:17], v[52:53], v[26:27]
	v_pk_mul_f32 v[18:19], v[54:55], v[24:25]
	global_store_dwordx4 v[14:15], v[16:19], off
	s_waitcnt vmcnt(7)
	v_lshlrev_b32_e32 v26, 16, v78
	v_and_b32_e32 v27, 0xffff0000, v78
	v_lshlrev_b32_e32 v24, 16, v79
	v_and_b32_e32 v25, 0xffff0000, v79
	v_pk_mul_f32 v[26:27], v[22:23], v[26:27] op_sel_hi:[0,1]
	v_pk_mul_f32 v[24:25], v[22:23], v[24:25] op_sel_hi:[0,1]
	v_pk_mul_f32 v[16:17], v[56:57], v[26:27]
	v_pk_mul_f32 v[18:19], v[58:59], v[24:25]
	global_store_dwordx4 v[14:15], v[16:19], off offset:1024
	s_waitcnt vmcnt(7)
	v_lshlrev_b32_e32 v26, 16, v80
	v_and_b32_e32 v27, 0xffff0000, v80
	v_lshlrev_b32_e32 v24, 16, v81
	v_and_b32_e32 v25, 0xffff0000, v81
	v_pk_mul_f32 v[26:27], v[22:23], v[26:27] op_sel_hi:[0,1]
	v_pk_mul_f32 v[24:25], v[22:23], v[24:25] op_sel_hi:[0,1]
	v_pk_mul_f32 v[16:17], v[60:61], v[26:27]
	v_pk_mul_f32 v[18:19], v[62:63], v[24:25]
	global_store_dwordx4 v[14:15], v[16:19], off offset:2048
	s_waitcnt vmcnt(7)
	v_lshlrev_b32_e32 v26, 16, v82
	v_and_b32_e32 v27, 0xffff0000, v82
	v_lshlrev_b32_e32 v24, 16, v83
	v_and_b32_e32 v25, 0xffff0000, v83
	s_cmpk_lt_i32 s2, 0x4000
	s_cbranch_scc0 .Lfin_nopf
	v_lshl_add_u64 v[16:17], s[4:5], 0, v[12:13]
	s_add_u32 s14, s4, s10
	s_addc_u32 s15, s5, s11
	v_add_co_u32_e32 v20, vcc, s12, v16
	s_nop 1
	v_addc_co_u32_e32 v21, vcc, 0, v17, vcc
	global_load_dwordx2 v[100:101], v1, s[14:15]
	global_load_dwordx2 v[68:69], v[20:21], off
	global_load_dwordx2 v[70:71], v[20:21], off offset:512
	global_load_dwordx2 v[72:73], v[20:21], off offset:1024
	global_load_dwordx2 v[74:75], v[20:21], off offset:1536
	global_load_dwordx2 v[76:77], v[20:21], off offset:2048
	global_load_dwordx2 v[78:79], v[20:21], off offset:2560
	global_load_dwordx2 v[80:81], v[20:21], off offset:3072
	global_load_dwordx2 v[82:83], v[20:21], off offset:3584
.Lfin_nopf:
	v_pk_mul_f32 v[26:27], v[22:23], v[26:27] op_sel_hi:[0,1]
	v_pk_mul_f32 v[24:25], v[22:23], v[24:25] op_sel_hi:[0,1]
	v_pk_mul_f32 v[16:17], v[64:65], v[26:27]
	v_pk_mul_f32 v[18:19], v[66:67], v[24:25]
	global_store_dwordx4 v[14:15], v[16:19], off offset:3072
	v_lshl_add_u64 v[14:15], v[14:15], 0, s[8:9]
	s_cmpk_lt_i32 s2, 0x4000
	s_cbranch_scc1 .LBB0_734
